# grid barrier: non-leader workgroups poll the cross-XCD release word directly instead of waiting for their XCD leader's relay
# speedup vs baseline: 1.0006x; 1.0006x over previous
.LBB0_28:
	s_mov_b64 s[10:11], exec
	v_mbcnt_lo_u32_b32 v1, s10, 0
	v_mbcnt_hi_u32_b32 v1, s11, v1
	v_cmp_eq_u32_e32 vcc, 0, v1
	s_and_saveexec_b64 s[6:7], vcc
	v_readlane_b32 s50, v252, 18
	v_readlane_b32 s51, v252, 19
	s_cbranch_execz .LBB0_30
	s_bcnt1_i32_b64 s4, s[10:11]
	v_readlane_b32 s10, v252, 12
	v_mov_b32_e32 v3, s4
	v_readlane_b32 s11, v252, 13
	s_nop 4
	global_atomic_add v3, v81, v3, s[10:11] sc0
